# attention tile bodies: all eight V fragment LDS reads of the PV part issued up front into fresh registers (the softmax temporaries) behind counted waits, instead of read -> lgkmcnt(0) -> 2 MFMA chains
# speedup vs baseline: 1.0080x; 1.0017x over previous
; DEVI unsigned pk_bf16(float lo, float hi) { unsigned r; asm("v_cvt_pk_bf16_f32 %0, %1, %2" : "=v"(r) : "v"(lo), "v"(hi)); return r; }
; DEVI bf16x8 mk8(uint2 a, uint2 b) { union { uint4 u; bf16x8 v; } c; c.u = make_uint4(a.x, a.y, b.x, b.y); return c.v; }
; template <int DK, bool BIAS> ...
;     ...
; #pragma unroll
;       for (int qi = 0; qi < 2; ++qi) {
;         float mx = -3e38f;
;         if (BIAS) {
; #pragma unroll
;           for (int kt = 0; kt < 4; ++kt) { const f32x4 nf = *(const f32x4*)(fkm + buf * 64 + 16 * kt + 4 * fq);
; #pragma unroll
;             for (int r = 0; r < 4; ++r) { const float t = fmaf(S[kt][qi][r], sc2, nf[r]); S[kt][qi][r] = t; mx = fmaxf(mx, t); } }
;         } else {
; #pragma unroll
;           for (int kt = 0; kt < 4; ++kt)
; #pragma unroll
;             for (int r = 0; r < 4; ++r) mx = fmaxf(mx, S[kt][qi][r]);
;           mx *= sc2;
;         }
;         mx = fmaxf(mx, __shfl_xor(mx, 16)); mx = fmaxf(mx, __shfl_xor(mx, 32));
;         const float mold = mrun[qi], mnew = fmaxf(mold, mx);
;         mrun[qi] = mnew;
;         float ps = 0.f;
; #pragma unroll
;         for (int kt = 0; kt < 4; ++kt)
; #pragma unroll
;           for (int r = 0; r < 4; ++r) { const float pv = BIAS ? __builtin_amdgcn_exp2f(S[kt][qi][r] - mnew) : __builtin_amdgcn_exp2f(fmaf(S[kt][qi][r], sc2, -mnew)); S[kt][qi][r] = pv; ps += pv; }
;         {
;           const float alpha = __builtin_amdgcn_exp2f(mold - mnew);
;           lrun[qi] *= alpha;
; #pragma unroll
;           for (int et = 0; et < 4; ++et) O[et][qi] *= alpha;
;         }
;         lrun[qi] += ps;
; #pragma unroll
;         for (int k2 = 0; k2 < 2; ++k2) { uint2 lo, hi; lo.x = pk_bf16(S[2 * k2][qi][0], S[2 * k2][qi][1]); lo.y = pk_bf16(S[2 * k2][qi][2], S[2 * k2][qi][3]);
;           hi.x = pk_bf16(S[2 * k2 + 1][qi][0], S[2 * k2 + 1][qi][1]); hi.y = pk_bf16(S[2 * k2 + 1][qi][2], S[2 * k2 + 1][qi][3]); pf[qi][k2] = mk8(lo, hi); }
;       }
; #pragma unroll
;       for (int k2 = 0; k2 < 2; ++k2)
; #pragma unroll
;         for (int et = 0; et < 4; ++et) {
;           const uint2 v0 = *(const uint2*)(Vtm + (buf * 64 + 16 * et + fr) * 72 + 32 * k2 + 4 * fq), v1 = *(const uint2*)(Vtm + (buf * 64 + 16 * et + fr) * 72 + 32 * k2 + 16 + 4 * fq);
;           const bf16x8 va = mk8(v0, v1);
.LBB0_1776:
	s_or_b64 exec, exec, s[18:19]
	ds_read_b128 v[174:177], v168 offset:36864
	ds_read_b128 v[194:197], v168 offset:36928
	ds_read_b128 v[242:245], v168 offset:36992
	ds_read_b128 v[246:249], v168 offset:37056
	s_mov_b32 s100, 0x3e38aa3b
	s_mov_b32 s101, 0x3e38aa3b
	v_lshlrev_b32_e32 v250, 2, v186
	s_waitcnt lgkmcnt(3)
	v_pk_fma_f32 v[210:211], v[80:81], s[100:101], v[174:175]
	v_pk_fma_f32 v[212:213], v[82:83], s[100:101], v[176:177]
	v_pk_fma_f32 v[226:227], v[64:65], s[100:101], v[174:175]
	v_pk_fma_f32 v[228:229], v[66:67], s[100:101], v[176:177]
	s_waitcnt lgkmcnt(2)
	v_pk_fma_f32 v[214:215], v[86:87], s[100:101], v[194:195]
	v_pk_fma_f32 v[216:217], v[88:89], s[100:101], v[196:197]
	v_pk_fma_f32 v[230:231], v[68:69], s[100:101], v[194:195]
	v_pk_fma_f32 v[232:233], v[70:71], s[100:101], v[196:197]
	s_waitcnt lgkmcnt(1)
	v_pk_fma_f32 v[218:219], v[90:91], s[100:101], v[242:243]
	v_pk_fma_f32 v[220:221], v[92:93], s[100:101], v[244:245]
	v_pk_fma_f32 v[234:235], v[72:73], s[100:101], v[242:243]
	v_pk_fma_f32 v[236:237], v[74:75], s[100:101], v[244:245]
	s_waitcnt lgkmcnt(0)
	v_pk_fma_f32 v[222:223], v[94:95], s[100:101], v[246:247]
	v_pk_fma_f32 v[224:225], v[96:97], s[100:101], v[248:249]
	v_pk_fma_f32 v[238:239], v[76:77], s[100:101], v[246:247]
	v_pk_fma_f32 v[240:241], v[78:79], s[100:101], v[248:249]
	v_max3_f32 v84, v210, s31, v211
	v_max3_f32 v85, v226, s31, v227
	v_max3_f32 v84, v84, v212, v213
	v_max3_f32 v85, v85, v228, v229
	v_max3_f32 v84, v84, v214, v215
	v_max3_f32 v85, v85, v230, v231
	v_max3_f32 v84, v84, v216, v217
	v_max3_f32 v85, v85, v232, v233
	v_max3_f32 v84, v84, v218, v219
	v_max3_f32 v85, v85, v234, v235
	v_max3_f32 v84, v84, v220, v221
	v_max3_f32 v85, v85, v236, v237
	v_max3_f32 v84, v84, v222, v223
	v_max3_f32 v85, v85, v238, v239
	v_max3_f32 v84, v84, v224, v225
	v_max3_f32 v85, v85, v240, v241
	ds_bpermute_b32 v86, v250, v84
	ds_bpermute_b32 v87, v250, v85
	s_waitcnt lgkmcnt(0)
	v_max_f32_e32 v84, v84, v86
	v_max_f32_e32 v85, v85, v87
	v_lshlrev_b32_e32 v250, 2, v185
	ds_bpermute_b32 v86, v250, v84
	ds_bpermute_b32 v87, v250, v85
	s_waitcnt lgkmcnt(0)
	v_max3_f32 v131, v114, v84, v86
	v_max3_f32 v173, v112, v85, v87
	v_sub_f32_e32 v84, v114, v131
	v_sub_f32_e32 v85, v112, v173
	v_exp_f32_e32 v126, v84
	v_exp_f32_e32 v82, v85
	v_sub_f32_e32 v86, 0, v131
	v_sub_f32_e32 v80, 0, v173
	v_pk_add_f32 v[210:211], v[210:211], v[86:87] op_sel_hi:[1,0]
	v_pk_add_f32 v[212:213], v[212:213], v[86:87] op_sel_hi:[1,0]
	v_pk_add_f32 v[226:227], v[226:227], v[80:81] op_sel_hi:[1,0]
	v_pk_add_f32 v[228:229], v[228:229], v[80:81] op_sel_hi:[1,0]
	v_pk_add_f32 v[214:215], v[214:215], v[86:87] op_sel_hi:[1,0]
	v_pk_add_f32 v[216:217], v[216:217], v[86:87] op_sel_hi:[1,0]
	v_pk_add_f32 v[230:231], v[230:231], v[80:81] op_sel_hi:[1,0]
	v_pk_add_f32 v[232:233], v[232:233], v[80:81] op_sel_hi:[1,0]
	v_pk_add_f32 v[218:219], v[218:219], v[86:87] op_sel_hi:[1,0]
	v_pk_add_f32 v[220:221], v[220:221], v[86:87] op_sel_hi:[1,0]
	v_pk_add_f32 v[234:235], v[234:235], v[80:81] op_sel_hi:[1,0]
	v_pk_add_f32 v[236:237], v[236:237], v[80:81] op_sel_hi:[1,0]
	v_pk_add_f32 v[222:223], v[222:223], v[86:87] op_sel_hi:[1,0]
	v_pk_add_f32 v[224:225], v[224:225], v[86:87] op_sel_hi:[1,0]
	v_pk_add_f32 v[238:239], v[238:239], v[80:81] op_sel_hi:[1,0]
	v_pk_add_f32 v[240:241], v[240:241], v[80:81] op_sel_hi:[1,0]
	v_exp_f32_e32 v155, v210
	v_exp_f32_e32 v154, v226
	v_exp_f32_e32 v157, v211
	v_exp_f32_e32 v156, v227
	v_exp_f32_e32 v151, v212
	v_exp_f32_e32 v150, v228
	v_exp_f32_e32 v153, v213
	v_exp_f32_e32 v152, v229
	v_exp_f32_e32 v117, v214
	v_exp_f32_e32 v116, v230
	v_exp_f32_e32 v119, v215
	v_exp_f32_e32 v118, v231
	v_exp_f32_e32 v123, v216
	v_exp_f32_e32 v122, v232
	v_exp_f32_e32 v121, v217
	v_exp_f32_e32 v120, v233
	v_exp_f32_e32 v125, v218
	v_exp_f32_e32 v124, v234
	v_exp_f32_e32 v89, v219
	v_exp_f32_e32 v88, v235
	v_exp_f32_e32 v95, v220
	v_exp_f32_e32 v94, v236
	v_exp_f32_e32 v115, v221
	v_exp_f32_e32 v114, v237
	v_exp_f32_e32 v93, v222
	v_exp_f32_e32 v92, v238
	v_exp_f32_e32 v113, v223
	v_exp_f32_e32 v112, v239
	v_exp_f32_e32 v91, v224
	v_exp_f32_e32 v90, v240
	v_exp_f32_e32 v97, v225
	v_exp_f32_e32 v96, v241
	v_add_u32_e32 v242, 0x4800, v170
	v_add_u32_e32 v243, 0x5000, v170
	v_add_u32_e32 v244, 0x5800, v170
	v_add_u32_e32 v245, 0x6000, v170
	ds_read2_b64 v[210:213], v242 offset1:4
	ds_read2_b64 v[214:217], v243 offset0:32 offset1:36
	ds_read2_b64 v[218:221], v244 offset0:64 offset1:68
	ds_read2_b64 v[222:225], v245 offset0:96 offset1:100
	ds_read2_b64 v[226:229], v242 offset0:8 offset1:12
	ds_read2_b64 v[230:233], v243 offset0:40 offset1:44
	ds_read2_b64 v[234:237], v244 offset0:72 offset1:76
	ds_read2_b64 v[238:241], v245 offset0:104 offset1:108
	v_pk_mul_f32 v[202:203], v[52:53], v[126:127] op_sel_hi:[1,0]
	v_pk_mul_f32 v[52:53], v[56:57], v[126:127] op_sel_hi:[1,0]
	v_pk_mul_f32 v[198:199], v[48:49], v[126:127] op_sel_hi:[1,0]
	v_pk_mul_f32 v[48:49], v[60:61], v[126:127] op_sel_hi:[1,0]
	v_pk_mul_f32 v[200:201], v[50:51], v[126:127] op_sel_hi:[1,0]
	v_pk_mul_f32 v[204:205], v[54:55], v[126:127] op_sel_hi:[1,0]
	v_pk_add_f32 v[64:65], v[154:155], 0 op_sel_hi:[1,0]
	v_pk_add_f32 v[80:81], v[156:157], v[64:65]
	v_pk_mul_f32 v[46:47], v[46:47], v[82:83] op_sel_hi:[1,0]
	v_pk_mul_f32 v[44:45], v[44:45], v[82:83] op_sel_hi:[1,0]
	v_pk_mul_f32 v[54:55], v[58:59], v[126:127] op_sel_hi:[1,0]
	v_cvt_pk_bf16_f32 v56, v155, v157
	v_cvt_pk_bf16_f32 v57, v151, v153
	v_cvt_pk_bf16_f32 v58, v117, v119
	v_cvt_pk_bf16_f32 v59, v123, v121
	v_cvt_pk_bf16_f32 v68, v154, v156
	s_waitcnt lgkmcnt(7)
; DEVI unsigned pk_bf16(float lo, float hi) { unsigned r; asm("v_cvt_pk_bf16_f32 %0, %1, %2" : "=v"(r) : "v"(lo), "v"(hi)); return r; }
; DEVI bf16x8 mk8(uint2 a, uint2 b) { union { uint4 u; bf16x8 v; } c; c.u = make_uint4(a.x, a.y, b.x, b.y); return c.v; }
; #define MFMA(a, b, c) __builtin_amdgcn_mfma_f32_16x16x32_bf16((a), (b), (c), 0, 0, 0)
; template <int DK, bool BIAS> ...
;     ...
;         float ps = 0.f;
; #pragma unroll
;         for (int kt = 0; kt < 4; ++kt)
; #pragma unroll
;           for (int r = 0; r < 4; ++r) { const float pv = BIAS ? __builtin_amdgcn_exp2f(S[kt][qi][r] - mnew) : __builtin_amdgcn_exp2f(fmaf(S[kt][qi][r], sc2, -mnew)); S[kt][qi][r] = pv; ps += pv; }
;         {
;           const float alpha = __builtin_amdgcn_exp2f(mold - mnew);
;           lrun[qi] *= alpha;
; #pragma unroll
;           for (int et = 0; et < 4; ++et) O[et][qi] *= alpha;
;         }
;         lrun[qi] += ps;
; #pragma unroll
;         for (int k2 = 0; k2 < 2; ++k2) { uint2 lo, hi; lo.x = pk_bf16(S[2 * k2][qi][0], S[2 * k2][qi][1]); lo.y = pk_bf16(S[2 * k2][qi][2], S[2 * k2][qi][3]);
;           hi.x = pk_bf16(S[2 * k2 + 1][qi][0], S[2 * k2 + 1][qi][1]); hi.y = pk_bf16(S[2 * k2 + 1][qi][2], S[2 * k2 + 1][qi][3]); pf[qi][k2] = mk8(lo, hi); }
;       }
; #pragma unroll
;       for (int k2 = 0; k2 < 2; ++k2)
; #pragma unroll
;         for (int et = 0; et < 4; ++et) {
;           const uint2 v0 = *(const uint2*)(Vtm + (buf * 64 + 16 * et + fr) * 72 + 32 * k2 + 4 * fq), v1 = *(const uint2*)(Vtm + (buf * 64 + 16 * et + fr) * 72 + 32 * k2 + 16 + 4 * fq);
;           const bf16x8 va = mk8(v0, v1);
; #pragma unroll
;           for (int qi = 0; qi < 2; ++qi) O[et][qi] = MFMA(va, pf[qi][k2], O[et][qi]);
;         }
	v_mfma_f32_16x16x32_bf16 v[76:79], v[210:213], v[56:59], v[198:201]
	v_cvt_pk_bf16_f32 v69, v150, v152
	v_cvt_pk_bf16_f32 v70, v116, v118
	v_cvt_pk_bf16_f32 v71, v122, v120
	v_pk_mul_f32 v[42:43], v[42:43], v[82:83] op_sel_hi:[1,0]
	s_nop 0
	v_mfma_f32_16x16x32_bf16 v[44:47], v[210:213], v[68:71], v[44:47]
	v_pk_mul_f32 v[40:41], v[40:41], v[82:83] op_sel_hi:[1,0]
	s_waitcnt lgkmcnt(6)
	v_mfma_f32_16x16x32_bf16 v[84:87], v[214:217], v[56:59], v[202:205]
	v_pk_mul_f32 v[50:51], v[62:63], v[126:127] op_sel_hi:[1,0]
	v_mfma_f32_16x16x32_bf16 v[40:43], v[214:217], v[68:71], v[40:43]
	v_pk_mul_f32 v[38:39], v[38:39], v[82:83] op_sel_hi:[1,0]
	v_pk_mul_f32 v[36:37], v[36:37], v[82:83] op_sel_hi:[1,0]
	s_waitcnt lgkmcnt(5)
	v_mfma_f32_16x16x32_bf16 v[154:157], v[218:221], v[56:59], v[52:55]
	v_pk_mul_f32 v[34:35], v[34:35], v[82:83] op_sel_hi:[1,0]
	v_pk_mul_f32 v[32:33], v[32:33], v[82:83] op_sel_hi:[1,0]
	v_cvt_pk_bf16_f32 v60, v125, v89
	v_mfma_f32_16x16x32_bf16 v[36:39], v[218:221], v[68:71], v[36:39]
	s_waitcnt lgkmcnt(4)
	v_mfma_f32_16x16x32_bf16 v[64:67], v[222:225], v[56:59], v[48:51]
	v_cvt_pk_bf16_f32 v61, v95, v115
	v_cvt_pk_bf16_f32 v62, v93, v113
	v_cvt_pk_bf16_f32 v63, v91, v97
	s_nop 0
	v_mfma_f32_16x16x32_bf16 v[32:35], v[222:225], v[68:71], v[32:35]
	v_cvt_pk_bf16_f32 v68, v124, v88
	v_cvt_pk_bf16_f32 v69, v94, v114
	s_waitcnt lgkmcnt(3)
	v_mfma_f32_16x16x32_bf16 v[48:51], v[226:229], v[60:63], v[76:79]
	v_cvt_pk_bf16_f32 v70, v92, v112
	v_cvt_pk_bf16_f32 v71, v90, v96
	s_nop 1
	v_mfma_f32_16x16x32_bf16 v[44:47], v[226:229], v[68:71], v[44:47]
	v_pk_add_f32 v[52:53], v[150:151], v[80:81]
	v_mov_b32_e32 v83, v126
	v_pk_add_f32 v[76:77], v[152:153], v[52:53]
	s_waitcnt lgkmcnt(2)
	v_mfma_f32_16x16x32_bf16 v[52:55], v[230:233], v[60:63], v[84:87]
	v_pk_add_f32 v[76:77], v[116:117], v[76:77]
	v_pk_add_f32 v[76:77], v[118:119], v[76:77]
	v_mfma_f32_16x16x32_bf16 v[40:43], v[230:233], v[68:71], v[40:43]
	v_pk_add_f32 v[76:77], v[122:123], v[76:77]
	v_pk_add_f32 v[56:57], v[120:121], v[76:77]
	v_pk_add_f32 v[80:81], v[124:125], v[56:57]
	s_waitcnt lgkmcnt(1)
	v_mfma_f32_16x16x32_bf16 v[56:59], v[234:237], v[60:63], v[154:157]
	v_pk_add_f32 v[80:81], v[88:89], v[80:81]
	v_pk_add_f32 v[80:81], v[94:95], v[80:81]
	v_mfma_f32_16x16x32_bf16 v[36:39], v[234:237], v[68:71], v[36:39]
	v_pk_add_f32 v[80:81], v[114:115], v[80:81]
	v_mov_b32_e32 v114, v131
	v_pk_add_f32 v[72:73], v[92:93], v[80:81]
	s_waitcnt lgkmcnt(0)
	v_mfma_f32_16x16x32_bf16 v[60:63], v[238:241], v[60:63], v[64:67]
	v_pk_add_f32 v[72:73], v[112:113], v[72:73]
	v_mov_b32_e32 v112, v173
	v_mfma_f32_16x16x32_bf16 v[32:35], v[238:241], v[68:71], v[32:35]
	v_pk_add_f32 v[64:65], v[90:91], v[72:73]
	v_pk_add_f32 v[64:65], v[96:97], v[64:65]
	s_nop 0
	v_pk_fma_f32 v[106:107], v[106:107], v[82:83], v[64:65]

; DEVI unsigned pk_bf16(float lo, float hi) { unsigned r; asm("v_cvt_pk_bf16_f32 %0, %1, %2" : "=v"(r) : "v"(lo), "v"(hi)); return r; }
; DEVI bf16x8 mk8(uint2 a, uint2 b) { union { uint4 u; bf16x8 v; } c; c.u = make_uint4(a.x, a.y, b.x, b.y); return c.v; }
; template <int DK, bool BIAS> ...
;     ...
; #pragma unroll
;       for (int qi = 0; qi < 2; ++qi) {
;         float mx = -3e38f;
;         if (BIAS) {
; #pragma unroll
;           for (int kt = 0; kt < 4; ++kt) { const f32x4 nf = *(const f32x4*)(fkm + buf * 64 + 16 * kt + 4 * fq);
; #pragma unroll
;             for (int r = 0; r < 4; ++r) { const float t = fmaf(S[kt][qi][r], sc2, nf[r]); S[kt][qi][r] = t; mx = fmaxf(mx, t); } }
;         } else {
; #pragma unroll
;           for (int kt = 0; kt < 4; ++kt)
; #pragma unroll
;             for (int r = 0; r < 4; ++r) mx = fmaxf(mx, S[kt][qi][r]);
;           mx *= sc2;
;         }
;         mx = fmaxf(mx, __shfl_xor(mx, 16)); mx = fmaxf(mx, __shfl_xor(mx, 32));
;         const float mold = mrun[qi], mnew = fmaxf(mold, mx);
;         mrun[qi] = mnew;
;         float ps = 0.f;
; #pragma unroll
;         for (int kt = 0; kt < 4; ++kt)
; #pragma unroll
;           for (int r = 0; r < 4; ++r) { const float pv = BIAS ? __builtin_amdgcn_exp2f(S[kt][qi][r] - mnew) : __builtin_amdgcn_exp2f(fmaf(S[kt][qi][r], sc2, -mnew)); S[kt][qi][r] = pv; ps += pv; }
;         {
;           const float alpha = __builtin_amdgcn_exp2f(mold - mnew);
;           lrun[qi] *= alpha;
; #pragma unroll
;           for (int et = 0; et < 4; ++et) O[et][qi] *= alpha;
;         }
;         lrun[qi] += ps;
; #pragma unroll
;         for (int k2 = 0; k2 < 2; ++k2) { uint2 lo, hi; lo.x = pk_bf16(S[2 * k2][qi][0], S[2 * k2][qi][1]); lo.y = pk_bf16(S[2 * k2][qi][2], S[2 * k2][qi][3]);
;           hi.x = pk_bf16(S[2 * k2 + 1][qi][0], S[2 * k2 + 1][qi][1]); hi.y = pk_bf16(S[2 * k2 + 1][qi][2], S[2 * k2 + 1][qi][3]); pf[qi][k2] = mk8(lo, hi); }
;       }
; #pragma unroll
;       for (int k2 = 0; k2 < 2; ++k2)
; #pragma unroll
;         for (int et = 0; et < 4; ++et) {
;           const uint2 v0 = *(const uint2*)(Vtm + (buf * 64 + 16 * et + fr) * 72 + 32 * k2 + 4 * fq), v1 = *(const uint2*)(Vtm + (buf * 64 + 16 * et + fr) * 72 + 32 * k2 + 16 + 4 * fq);
;           const bf16x8 va = mk8(v0, v1);
.LBB0_1797:
	s_or_b64 exec, exec, s[18:19]
	ds_read_b128 v[174:177], v104 offset:37120
	ds_read_b128 v[194:197], v104 offset:37184
	ds_read_b128 v[242:245], v104 offset:37248
	ds_read_b128 v[246:249], v104 offset:37312
	s_mov_b32 s100, 0x3e38aa3b
	s_mov_b32 s101, 0x3e38aa3b
	v_lshlrev_b32_e32 v250, 2, v186
	s_waitcnt lgkmcnt(3)
	v_pk_fma_f32 v[210:211], v[80:81], s[100:101], v[174:175]
	v_pk_fma_f32 v[212:213], v[82:83], s[100:101], v[176:177]
	v_pk_fma_f32 v[226:227], v[64:65], s[100:101], v[174:175]
	v_pk_fma_f32 v[228:229], v[66:67], s[100:101], v[176:177]
	s_waitcnt lgkmcnt(2)
	v_pk_fma_f32 v[214:215], v[86:87], s[100:101], v[194:195]
	v_pk_fma_f32 v[216:217], v[88:89], s[100:101], v[196:197]
	v_pk_fma_f32 v[230:231], v[68:69], s[100:101], v[194:195]
	v_pk_fma_f32 v[232:233], v[70:71], s[100:101], v[196:197]
	s_waitcnt lgkmcnt(1)
	v_pk_fma_f32 v[218:219], v[90:91], s[100:101], v[242:243]
	v_pk_fma_f32 v[220:221], v[92:93], s[100:101], v[244:245]
	v_pk_fma_f32 v[234:235], v[72:73], s[100:101], v[242:243]
	v_pk_fma_f32 v[236:237], v[74:75], s[100:101], v[244:245]
	s_waitcnt lgkmcnt(0)
	v_pk_fma_f32 v[222:223], v[94:95], s[100:101], v[246:247]
	v_pk_fma_f32 v[224:225], v[96:97], s[100:101], v[248:249]
	v_pk_fma_f32 v[238:239], v[76:77], s[100:101], v[246:247]
	v_pk_fma_f32 v[240:241], v[78:79], s[100:101], v[248:249]
	v_max3_f32 v84, v210, s31, v211
	v_max3_f32 v85, v226, s31, v227
	v_max3_f32 v84, v84, v212, v213
	v_max3_f32 v85, v85, v228, v229
	v_max3_f32 v84, v84, v214, v215
	v_max3_f32 v85, v85, v230, v231
	v_max3_f32 v84, v84, v216, v217
	v_max3_f32 v85, v85, v232, v233
	v_max3_f32 v84, v84, v218, v219
	v_max3_f32 v85, v85, v234, v235
	v_max3_f32 v84, v84, v220, v221
	v_max3_f32 v85, v85, v236, v237
	v_max3_f32 v84, v84, v222, v223
	v_max3_f32 v85, v85, v238, v239
	v_max3_f32 v84, v84, v224, v225
	v_max3_f32 v85, v85, v240, v241
	ds_bpermute_b32 v86, v250, v84
	ds_bpermute_b32 v87, v250, v85
	s_waitcnt lgkmcnt(0)
	v_max_f32_e32 v84, v84, v86
	v_max_f32_e32 v85, v85, v87
	v_lshlrev_b32_e32 v250, 2, v185
	ds_bpermute_b32 v86, v250, v84
	ds_bpermute_b32 v87, v250, v85
	s_waitcnt lgkmcnt(0)
	v_max3_f32 v131, v114, v84, v86
	v_max3_f32 v173, v112, v85, v87
	v_sub_f32_e32 v84, v114, v131
	v_sub_f32_e32 v85, v112, v173
	v_exp_f32_e32 v126, v84
	v_exp_f32_e32 v82, v85
	v_sub_f32_e32 v86, 0, v131
	v_sub_f32_e32 v80, 0, v173
	v_pk_add_f32 v[210:211], v[210:211], v[86:87] op_sel_hi:[1,0]
	v_pk_add_f32 v[212:213], v[212:213], v[86:87] op_sel_hi:[1,0]
	v_pk_add_f32 v[226:227], v[226:227], v[80:81] op_sel_hi:[1,0]
	v_pk_add_f32 v[228:229], v[228:229], v[80:81] op_sel_hi:[1,0]
	v_pk_add_f32 v[214:215], v[214:215], v[86:87] op_sel_hi:[1,0]
	v_pk_add_f32 v[216:217], v[216:217], v[86:87] op_sel_hi:[1,0]
	v_pk_add_f32 v[230:231], v[230:231], v[80:81] op_sel_hi:[1,0]
	v_pk_add_f32 v[232:233], v[232:233], v[80:81] op_sel_hi:[1,0]
	v_pk_add_f32 v[218:219], v[218:219], v[86:87] op_sel_hi:[1,0]
	v_pk_add_f32 v[220:221], v[220:221], v[86:87] op_sel_hi:[1,0]
	v_pk_add_f32 v[234:235], v[234:235], v[80:81] op_sel_hi:[1,0]
	v_pk_add_f32 v[236:237], v[236:237], v[80:81] op_sel_hi:[1,0]
	v_pk_add_f32 v[222:223], v[222:223], v[86:87] op_sel_hi:[1,0]
	v_pk_add_f32 v[224:225], v[224:225], v[86:87] op_sel_hi:[1,0]
	v_pk_add_f32 v[238:239], v[238:239], v[80:81] op_sel_hi:[1,0]
	v_pk_add_f32 v[240:241], v[240:241], v[80:81] op_sel_hi:[1,0]
	v_exp_f32_e32 v155, v210
	v_exp_f32_e32 v154, v226
	v_exp_f32_e32 v157, v211
	v_exp_f32_e32 v156, v227
	v_exp_f32_e32 v151, v212
	v_exp_f32_e32 v150, v228
	v_exp_f32_e32 v153, v213
	v_exp_f32_e32 v152, v229
	v_exp_f32_e32 v117, v214
	v_exp_f32_e32 v116, v230
	v_exp_f32_e32 v119, v215
	v_exp_f32_e32 v118, v231
	v_exp_f32_e32 v123, v216
	v_exp_f32_e32 v122, v232
	v_exp_f32_e32 v121, v217
	v_exp_f32_e32 v120, v233
	v_exp_f32_e32 v125, v218
	v_exp_f32_e32 v124, v234
	v_exp_f32_e32 v89, v219
	v_exp_f32_e32 v88, v235
	v_exp_f32_e32 v95, v220
	v_exp_f32_e32 v94, v236
	v_exp_f32_e32 v115, v221
	v_exp_f32_e32 v114, v237
	v_exp_f32_e32 v93, v222
	v_exp_f32_e32 v92, v238
	v_exp_f32_e32 v113, v223
	v_exp_f32_e32 v112, v239
	v_exp_f32_e32 v91, v224
	v_exp_f32_e32 v90, v240
	v_exp_f32_e32 v97, v225
	v_exp_f32_e32 v96, v241
	v_add_u32_e32 v242, 0x6800, v170
	v_add_u32_e32 v243, 0x7000, v170
	v_add_u32_e32 v244, 0x7800, v170
	v_add_u32_e32 v245, 0x8000, v170
	ds_read2_b64 v[210:213], v242 offset0:128 offset1:132
	ds_read2_b64 v[214:217], v243 offset0:160 offset1:164
	ds_read2_b64 v[218:221], v244 offset0:192 offset1:196
	ds_read2_b64 v[222:225], v245 offset0:224 offset1:228
	ds_read2_b64 v[226:229], v242 offset0:136 offset1:140
	ds_read2_b64 v[230:233], v243 offset0:168 offset1:172
	ds_read2_b64 v[234:237], v244 offset0:200 offset1:204
	ds_read2_b64 v[238:241], v245 offset0:232 offset1:236
	v_pk_mul_f32 v[202:203], v[52:53], v[126:127] op_sel_hi:[1,0]
	v_pk_mul_f32 v[52:53], v[56:57], v[126:127] op_sel_hi:[1,0]
	v_pk_mul_f32 v[198:199], v[48:49], v[126:127] op_sel_hi:[1,0]
	v_pk_mul_f32 v[48:49], v[60:61], v[126:127] op_sel_hi:[1,0]
	v_pk_mul_f32 v[200:201], v[50:51], v[126:127] op_sel_hi:[1,0]
	v_pk_mul_f32 v[204:205], v[54:55], v[126:127] op_sel_hi:[1,0]
	v_pk_add_f32 v[64:65], v[154:155], 0 op_sel_hi:[1,0]
	v_pk_add_f32 v[80:81], v[156:157], v[64:65]
	v_pk_mul_f32 v[46:47], v[46:47], v[82:83] op_sel_hi:[1,0]
	v_pk_mul_f32 v[44:45], v[44:45], v[82:83] op_sel_hi:[1,0]
	v_pk_mul_f32 v[54:55], v[58:59], v[126:127] op_sel_hi:[1,0]
	v_cvt_pk_bf16_f32 v56, v155, v157
	v_cvt_pk_bf16_f32 v57, v151, v153
	v_cvt_pk_bf16_f32 v58, v117, v119
	v_cvt_pk_bf16_f32 v59, v123, v121
	v_cvt_pk_bf16_f32 v68, v154, v156
	s_waitcnt lgkmcnt(7)
; DEVI unsigned pk_bf16(float lo, float hi) { unsigned r; asm("v_cvt_pk_bf16_f32 %0, %1, %2" : "=v"(r) : "v"(lo), "v"(hi)); return r; }
; DEVI bf16x8 mk8(uint2 a, uint2 b) { union { uint4 u; bf16x8 v; } c; c.u = make_uint4(a.x, a.y, b.x, b.y); return c.v; }
; #define MFMA(a, b, c) __builtin_amdgcn_mfma_f32_16x16x32_bf16((a), (b), (c), 0, 0, 0)
; template <int DK, bool BIAS> ...
;     ...
;         float ps = 0.f;
; #pragma unroll
;         for (int kt = 0; kt < 4; ++kt)
; #pragma unroll
;           for (int r = 0; r < 4; ++r) { const float pv = BIAS ? __builtin_amdgcn_exp2f(S[kt][qi][r] - mnew) : __builtin_amdgcn_exp2f(fmaf(S[kt][qi][r], sc2, -mnew)); S[kt][qi][r] = pv; ps += pv; }
;         {
;           const float alpha = __builtin_amdgcn_exp2f(mold - mnew);
;           lrun[qi] *= alpha;
; #pragma unroll
;           for (int et = 0; et < 4; ++et) O[et][qi] *= alpha;
;         }
;         lrun[qi] += ps;
; #pragma unroll
;         for (int k2 = 0; k2 < 2; ++k2) { uint2 lo, hi; lo.x = pk_bf16(S[2 * k2][qi][0], S[2 * k2][qi][1]); lo.y = pk_bf16(S[2 * k2][qi][2], S[2 * k2][qi][3]);
;           hi.x = pk_bf16(S[2 * k2 + 1][qi][0], S[2 * k2 + 1][qi][1]); hi.y = pk_bf16(S[2 * k2 + 1][qi][2], S[2 * k2 + 1][qi][3]); pf[qi][k2] = mk8(lo, hi); }
;       }
; #pragma unroll
;       for (int k2 = 0; k2 < 2; ++k2)
; #pragma unroll
;         for (int et = 0; et < 4; ++et) {
;           const uint2 v0 = *(const uint2*)(Vtm + (buf * 64 + 16 * et + fr) * 72 + 32 * k2 + 4 * fq), v1 = *(const uint2*)(Vtm + (buf * 64 + 16 * et + fr) * 72 + 32 * k2 + 16 + 4 * fq);
;           const bf16x8 va = mk8(v0, v1);
; #pragma unroll
;           for (int qi = 0; qi < 2; ++qi) O[et][qi] = MFMA(va, pf[qi][k2], O[et][qi]);
;         }
	v_mfma_f32_16x16x32_bf16 v[76:79], v[210:213], v[56:59], v[198:201]
	v_cvt_pk_bf16_f32 v69, v150, v152
	v_cvt_pk_bf16_f32 v70, v116, v118
	v_cvt_pk_bf16_f32 v71, v122, v120
	v_pk_mul_f32 v[42:43], v[42:43], v[82:83] op_sel_hi:[1,0]
	s_nop 0
	v_mfma_f32_16x16x32_bf16 v[44:47], v[210:213], v[68:71], v[44:47]
	v_pk_mul_f32 v[40:41], v[40:41], v[82:83] op_sel_hi:[1,0]
	s_waitcnt lgkmcnt(6)
	v_mfma_f32_16x16x32_bf16 v[84:87], v[214:217], v[56:59], v[202:205]
	v_pk_mul_f32 v[50:51], v[62:63], v[126:127] op_sel_hi:[1,0]
	v_mfma_f32_16x16x32_bf16 v[40:43], v[214:217], v[68:71], v[40:43]
	v_pk_mul_f32 v[38:39], v[38:39], v[82:83] op_sel_hi:[1,0]
	v_pk_mul_f32 v[36:37], v[36:37], v[82:83] op_sel_hi:[1,0]
	s_waitcnt lgkmcnt(5)
	v_mfma_f32_16x16x32_bf16 v[154:157], v[218:221], v[56:59], v[52:55]
	v_pk_mul_f32 v[34:35], v[34:35], v[82:83] op_sel_hi:[1,0]
	v_pk_mul_f32 v[32:33], v[32:33], v[82:83] op_sel_hi:[1,0]
	v_cvt_pk_bf16_f32 v60, v125, v89
	v_mfma_f32_16x16x32_bf16 v[36:39], v[218:221], v[68:71], v[36:39]
	s_waitcnt lgkmcnt(4)
	v_mfma_f32_16x16x32_bf16 v[64:67], v[222:225], v[56:59], v[48:51]
	v_cvt_pk_bf16_f32 v61, v95, v115
	v_cvt_pk_bf16_f32 v62, v93, v113
	v_cvt_pk_bf16_f32 v63, v91, v97
	s_nop 0
	v_mfma_f32_16x16x32_bf16 v[32:35], v[222:225], v[68:71], v[32:35]
	v_cvt_pk_bf16_f32 v68, v124, v88
	v_cvt_pk_bf16_f32 v69, v94, v114
	s_waitcnt lgkmcnt(3)
	v_mfma_f32_16x16x32_bf16 v[48:51], v[226:229], v[60:63], v[76:79]
	v_cvt_pk_bf16_f32 v70, v92, v112
	v_cvt_pk_bf16_f32 v71, v90, v96
	s_nop 1
	v_mfma_f32_16x16x32_bf16 v[44:47], v[226:229], v[68:71], v[44:47]
	v_pk_add_f32 v[52:53], v[150:151], v[80:81]
	v_mov_b32_e32 v83, v126
	v_pk_add_f32 v[76:77], v[152:153], v[52:53]
	s_waitcnt lgkmcnt(2)
	v_mfma_f32_16x16x32_bf16 v[52:55], v[230:233], v[60:63], v[84:87]
	v_pk_add_f32 v[76:77], v[116:117], v[76:77]
	v_pk_add_f32 v[76:77], v[118:119], v[76:77]
	v_mfma_f32_16x16x32_bf16 v[40:43], v[230:233], v[68:71], v[40:43]
	v_pk_add_f32 v[76:77], v[122:123], v[76:77]
	v_pk_add_f32 v[56:57], v[120:121], v[76:77]
	v_pk_add_f32 v[80:81], v[124:125], v[56:57]
	s_waitcnt lgkmcnt(1)
	v_mfma_f32_16x16x32_bf16 v[56:59], v[234:237], v[60:63], v[154:157]
	v_pk_add_f32 v[80:81], v[88:89], v[80:81]
	v_pk_add_f32 v[80:81], v[94:95], v[80:81]
	v_mfma_f32_16x16x32_bf16 v[36:39], v[234:237], v[68:71], v[36:39]
	v_pk_add_f32 v[80:81], v[114:115], v[80:81]
	v_mov_b32_e32 v114, v131
	v_pk_add_f32 v[72:73], v[92:93], v[80:81]
	s_waitcnt lgkmcnt(0)
	v_mfma_f32_16x16x32_bf16 v[60:63], v[238:241], v[60:63], v[64:67]
	v_pk_add_f32 v[72:73], v[112:113], v[72:73]
	v_mov_b32_e32 v112, v173
	v_mfma_f32_16x16x32_bf16 v[32:35], v[238:241], v[68:71], v[32:35]
	v_pk_add_f32 v[64:65], v[90:91], v[72:73]
	v_pk_add_f32 v[64:65], v[96:97], v[64:65]
	s_nop 0
	v_pk_fma_f32 v[106:107], v[106:107], v[82:83], v[64:65]

; DEVI unsigned pk_bf16(float lo, float hi) { unsigned r; asm("v_cvt_pk_bf16_f32 %0, %1, %2" : "=v"(r) : "v"(lo), "v"(hi)); return r; }
; DEVI bf16x8 mk8(uint2 a, uint2 b) { union { uint4 u; bf16x8 v; } c; c.u = make_uint4(a.x, a.y, b.x, b.y); return c.v; }
; template <int DK, bool BIAS> ...
;     ...
; #pragma unroll
;       for (int qi = 0; qi < 2; ++qi) {
;         float mx = -3e38f;
;         if (BIAS) {
; #pragma unroll
;           for (int kt = 0; kt < 4; ++kt) { const f32x4 nf = *(const f32x4*)(fkm + buf * 64 + 16 * kt + 4 * fq);
; #pragma unroll
;             for (int r = 0; r < 4; ++r) { const float t = fmaf(S[kt][qi][r], sc2, nf[r]); S[kt][qi][r] = t; mx = fmaxf(mx, t); } }
;         } else {
; #pragma unroll
;           for (int kt = 0; kt < 4; ++kt)
; #pragma unroll
;             for (int r = 0; r < 4; ++r) mx = fmaxf(mx, S[kt][qi][r]);
;           mx *= sc2;
;         }
;         mx = fmaxf(mx, __shfl_xor(mx, 16)); mx = fmaxf(mx, __shfl_xor(mx, 32));
;         const float mold = mrun[qi], mnew = fmaxf(mold, mx);
;         mrun[qi] = mnew;
;         float ps = 0.f;
; #pragma unroll
;         for (int kt = 0; kt < 4; ++kt)
; #pragma unroll
;           for (int r = 0; r < 4; ++r) { const float pv = BIAS ? __builtin_amdgcn_exp2f(S[kt][qi][r] - mnew) : __builtin_amdgcn_exp2f(fmaf(S[kt][qi][r], sc2, -mnew)); S[kt][qi][r] = pv; ps += pv; }
;         {
;           const float alpha = __builtin_amdgcn_exp2f(mold - mnew);
;           lrun[qi] *= alpha;
; #pragma unroll
;           for (int et = 0; et < 4; ++et) O[et][qi] *= alpha;
;         }
;         lrun[qi] += ps;
; #pragma unroll
;         for (int k2 = 0; k2 < 2; ++k2) { uint2 lo, hi; lo.x = pk_bf16(S[2 * k2][qi][0], S[2 * k2][qi][1]); lo.y = pk_bf16(S[2 * k2][qi][2], S[2 * k2][qi][3]);
;           hi.x = pk_bf16(S[2 * k2 + 1][qi][0], S[2 * k2 + 1][qi][1]); hi.y = pk_bf16(S[2 * k2 + 1][qi][2], S[2 * k2 + 1][qi][3]); pf[qi][k2] = mk8(lo, hi); }
;       }
; #pragma unroll
;       for (int k2 = 0; k2 < 2; ++k2)
; #pragma unroll
;         for (int et = 0; et < 4; ++et) {
;           const uint2 v0 = *(const uint2*)(Vtm + (buf * 64 + 16 * et + fr) * 72 + 32 * k2 + 4 * fq), v1 = *(const uint2*)(Vtm + (buf * 64 + 16 * et + fr) * 72 + 32 * k2 + 16 + 4 * fq);
;           const bf16x8 va = mk8(v0, v1);
.LBB0_1866:
	s_or_b64 exec, exec, s[18:19]
	s_mov_b32 s100, s34
	s_mov_b32 s101, s34
	v_lshlrev_b32_e32 v250, 2, v186
	v_max3_f32 v242, v96, s31, v97
	v_max3_f32 v243, v84, s31, v85
	v_max3_f32 v242, v242, v98, v99
	v_max3_f32 v243, v243, v86, v87
	v_max3_f32 v242, v242, v100, v101
	v_max3_f32 v243, v243, v88, v89
	v_max3_f32 v242, v242, v102, v103
	v_max3_f32 v243, v243, v90, v91
	v_max3_f32 v242, v242, v104, v105
	v_max3_f32 v243, v243, v80, v81
	v_max3_f32 v242, v242, v106, v107
	v_max3_f32 v243, v243, v82, v83
	v_max3_f32 v242, v242, v108, v109
	v_max3_f32 v243, v243, v92, v93
	v_max3_f32 v242, v242, v110, v111
	v_max3_f32 v243, v243, v94, v95
	v_mul_f32_e32 v242, 0x3e16c740, v242
	v_mul_f32_e32 v243, 0x3e16c740, v243
	ds_bpermute_b32 v244, v250, v242
	ds_bpermute_b32 v245, v250, v243
	s_waitcnt lgkmcnt(0)
	v_max_f32_e32 v242, v242, v244
	v_max_f32_e32 v243, v243, v245
	v_lshlrev_b32_e32 v250, 2, v185
	ds_bpermute_b32 v244, v250, v242
	ds_bpermute_b32 v245, v250, v243
	s_waitcnt lgkmcnt(0)
	v_max3_f32 v131, v154, v242, v244
	v_max3_f32 v209, v208, v243, v245
	v_sub_f32_e32 v242, v154, v131
	v_sub_f32_e32 v243, v208, v209
	v_sub_f32_e32 v246, 0, v131
	v_sub_f32_e32 v248, 0, v209
	v_pk_fma_f32 v[210:211], v[96:97], s[100:101], v[246:247] op_sel_hi:[1,1,0]
	v_pk_fma_f32 v[226:227], v[80:81], s[100:101], v[248:249] op_sel_hi:[1,1,0]
	v_pk_fma_f32 v[212:213], v[98:99], s[100:101], v[246:247] op_sel_hi:[1,1,0]
	v_pk_fma_f32 v[228:229], v[82:83], s[100:101], v[248:249] op_sel_hi:[1,1,0]
	v_pk_fma_f32 v[214:215], v[100:101], s[100:101], v[246:247] op_sel_hi:[1,1,0]
	v_pk_fma_f32 v[230:231], v[84:85], s[100:101], v[248:249] op_sel_hi:[1,1,0]
	v_pk_fma_f32 v[216:217], v[102:103], s[100:101], v[246:247] op_sel_hi:[1,1,0]
	v_pk_fma_f32 v[232:233], v[86:87], s[100:101], v[248:249] op_sel_hi:[1,1,0]
	v_pk_fma_f32 v[218:219], v[104:105], s[100:101], v[246:247] op_sel_hi:[1,1,0]
	v_pk_fma_f32 v[234:235], v[88:89], s[100:101], v[248:249] op_sel_hi:[1,1,0]
	v_pk_fma_f32 v[220:221], v[106:107], s[100:101], v[246:247] op_sel_hi:[1,1,0]
	v_pk_fma_f32 v[236:237], v[90:91], s[100:101], v[248:249] op_sel_hi:[1,1,0]
	v_pk_fma_f32 v[222:223], v[108:109], s[100:101], v[246:247] op_sel_hi:[1,1,0]
	v_pk_fma_f32 v[238:239], v[92:93], s[100:101], v[248:249] op_sel_hi:[1,1,0]
	v_pk_fma_f32 v[224:225], v[110:111], s[100:101], v[246:247] op_sel_hi:[1,1,0]
	v_pk_fma_f32 v[240:241], v[94:95], s[100:101], v[248:249] op_sel_hi:[1,1,0]
	v_exp_f32_e32 v178, v242
	v_exp_f32_e32 v90, v243
	v_exp_f32_e32 v163, v210
	v_exp_f32_e32 v170, v226
	v_exp_f32_e32 v165, v211
	v_exp_f32_e32 v104, v227
	v_exp_f32_e32 v167, v212
	v_exp_f32_e32 v172, v228
	v_exp_f32_e32 v169, v213
	v_exp_f32_e32 v106, v229
	v_exp_f32_e32 v155, v214
	v_exp_f32_e32 v162, v230
	v_exp_f32_e32 v157, v215
	v_exp_f32_e32 v164, v231
	v_exp_f32_e32 v159, v216
	v_exp_f32_e32 v166, v232
	v_exp_f32_e32 v161, v217
	v_exp_f32_e32 v168, v233
	v_exp_f32_e32 v171, v218
	v_exp_f32_e32 v154, v234
	v_exp_f32_e32 v105, v219
	v_exp_f32_e32 v156, v235
	v_exp_f32_e32 v173, v220
	v_exp_f32_e32 v158, v236
	v_exp_f32_e32 v107, v221
	v_exp_f32_e32 v160, v237
	v_exp_f32_e32 v175, v222
	v_exp_f32_e32 v174, v238
	v_exp_f32_e32 v109, v223
	v_exp_f32_e32 v108, v239
	v_exp_f32_e32 v177, v224
	v_exp_f32_e32 v176, v240
	v_exp_f32_e32 v111, v225
	v_exp_f32_e32 v110, v241
	v_add_u32_e32 v242, 0x6800, v203
	v_add_u32_e32 v243, 0x7000, v203
	v_add_u32_e32 v244, 0x7800, v203
	v_add_u32_e32 v245, 0x8000, v203
	ds_read2_b64 v[210:213], v242 offset1:4
	ds_read2_b64 v[214:217], v243 offset0:32 offset1:36
	ds_read2_b64 v[218:221], v244 offset0:64 offset1:68
	ds_read2_b64 v[222:225], v245 offset0:96 offset1:100
	ds_read2_b64 v[226:229], v243 offset0:40 offset1:44
	ds_read2_b64 v[230:233], v242 offset0:8 offset1:12
	ds_read2_b64 v[234:237], v244 offset0:72 offset1:76
	ds_read2_b64 v[238:241], v245 offset0:104 offset1:108
	v_pk_add_f32 v[80:81], v[154:155], 0 op_sel_hi:[1,0]
	v_pk_add_f32 v[80:81], v[156:157], v[80:81]
	v_pk_add_f32 v[80:81], v[158:159], v[80:81]
	v_pk_add_f32 v[80:81], v[160:161], v[80:81]
	v_pk_add_f32 v[80:81], v[162:163], v[80:81]
	v_pk_mul_f32 v[102:103], v[66:67], v[178:179] op_sel_hi:[1,0]
	v_pk_add_f32 v[80:81], v[164:165], v[80:81]
	v_pk_mul_f32 v[100:101], v[64:65], v[178:179] op_sel_hi:[1,0]
	v_pk_add_f32 v[80:81], v[166:167], v[80:81]
	v_pk_mul_f32 v[64:65], v[76:77], v[178:179] op_sel_hi:[1,0]
	v_pk_add_f32 v[80:81], v[168:169], v[80:81]
	v_cvt_pk_bf16_f32 v76, v171, v105
	v_pk_mul_f32 v[98:99], v[70:71], v[178:179] op_sel_hi:[1,0]
	v_pk_add_f32 v[80:81], v[170:171], v[80:81]
	v_pk_mul_f32 v[96:97], v[68:69], v[178:179] op_sel_hi:[1,0]
	v_pk_add_f32 v[88:89], v[104:105], v[80:81]
	v_cvt_pk_bf16_f32 v68, v155, v157
	v_cvt_pk_bf16_f32 v69, v159, v161
	v_pk_mul_f32 v[84:85], v[52:53], v[90:91] op_sel_hi:[1,0]
	v_pk_add_f32 v[52:53], v[172:173], v[88:89]
	v_pk_mul_f32 v[82:83], v[50:51], v[90:91] op_sel_hi:[1,0]
	v_pk_add_f32 v[52:53], v[106:107], v[52:53]
	v_pk_mul_f32 v[80:81], v[48:49], v[90:91] op_sel_hi:[1,0]
	v_pk_add_f32 v[52:53], v[174:175], v[52:53]
	v_pk_mul_f32 v[86:87], v[54:55], v[90:91] op_sel_hi:[1,0]
	v_pk_add_f32 v[52:53], v[108:109], v[52:53]
	v_pk_mul_f32 v[58:59], v[58:59], v[90:91] op_sel_hi:[1,0]
	v_pk_add_f32 v[52:53], v[176:177], v[52:53]
	v_pk_mul_f32 v[56:57], v[56:57], v[90:91] op_sel_hi:[1,0]
	v_pk_mul_f32 v[50:51], v[62:63], v[90:91] op_sel_hi:[1,0]
	v_pk_mul_f32 v[48:49], v[60:61], v[90:91] op_sel_hi:[1,0]
	v_mov_b32_e32 v91, v178
	v_pk_add_f32 v[52:53], v[110:111], v[52:53]
	v_cvt_pk_bf16_f32 v60, v170, v104
	v_pk_fma_f32 v[120:121], v[120:121], v[90:91], v[52:53]
	v_cvt_pk_bf16_f32 v70, v163, v165
	v_cvt_pk_bf16_f32 v71, v167, v169
	v_cvt_pk_bf16_f32 v52, v154, v156
	v_cvt_pk_bf16_f32 v53, v158, v160
	v_cvt_pk_bf16_f32 v54, v162, v164
	v_cvt_pk_bf16_f32 v55, v166, v168
	v_cvt_pk_bf16_f32 v61, v172, v106
	s_waitcnt lgkmcnt(7)
; DEVI unsigned pk_bf16(float lo, float hi) { unsigned r; asm("v_cvt_pk_bf16_f32 %0, %1, %2" : "=v"(r) : "v"(lo), "v"(hi)); return r; }
; DEVI bf16x8 mk8(uint2 a, uint2 b) { union { uint4 u; bf16x8 v; } c; c.u = make_uint4(a.x, a.y, b.x, b.y); return c.v; }
; #define MFMA(a, b, c) __builtin_amdgcn_mfma_f32_16x16x32_bf16((a), (b), (c), 0, 0, 0)
; template <int DK, bool BIAS> ...
;     ...
;         for (int k2 = 0; k2 < 2; ++k2) { uint2 lo, hi; lo.x = pk_bf16(S[2 * k2][qi][0], S[2 * k2][qi][1]); lo.y = pk_bf16(S[2 * k2][qi][2], S[2 * k2][qi][3]);
;           hi.x = pk_bf16(S[2 * k2 + 1][qi][0], S[2 * k2 + 1][qi][1]); hi.y = pk_bf16(S[2 * k2 + 1][qi][2], S[2 * k2 + 1][qi][3]); pf[qi][k2] = mk8(lo, hi); }
;       }
; #pragma unroll
;       for (int k2 = 0; k2 < 2; ++k2)
; #pragma unroll
;         for (int et = 0; et < 4; ++et) {
;           const uint2 v0 = *(const uint2*)(Vtm + (buf * 64 + 16 * et + fr) * 72 + 32 * k2 + 4 * fq), v1 = *(const uint2*)(Vtm + (buf * 64 + 16 * et + fr) * 72 + 32 * k2 + 16 + 4 * fq);
;           const bf16x8 va = mk8(v0, v1);
; #pragma unroll
;           for (int qi = 0; qi < 2; ++qi) O[et][qi] = MFMA(va, pf[qi][k2], O[et][qi]);
;         }
	v_mfma_f32_16x16x32_bf16 v[92:95], v[210:213], v[68:71], v[100:103]
	v_pk_mul_f32 v[74:75], v[74:75], v[178:179] op_sel_hi:[1,0]
	v_pk_mul_f32 v[72:73], v[72:73], v[178:179] op_sel_hi:[1,0]
	v_mfma_f32_16x16x32_bf16 v[80:83], v[210:213], v[52:55], v[80:83]
	v_cvt_pk_bf16_f32 v77, v173, v107
	s_waitcnt lgkmcnt(6)
	v_mfma_f32_16x16x32_bf16 v[96:99], v[214:217], v[68:71], v[96:99]
	v_pk_mul_f32 v[66:67], v[78:79], v[178:179] op_sel_hi:[1,0]
	v_cvt_pk_bf16_f32 v78, v175, v109
	v_cvt_pk_bf16_f32 v79, v177, v111
	v_mfma_f32_16x16x32_bf16 v[84:87], v[214:217], v[52:55], v[84:87]
	v_cvt_pk_bf16_f32 v62, v174, v108
	v_cvt_pk_bf16_f32 v63, v176, v110
	s_waitcnt lgkmcnt(5)
	v_mfma_f32_16x16x32_bf16 v[72:75], v[218:221], v[68:71], v[72:75]
	v_mov_b32_e32 v208, v209
	v_mov_b32_e32 v154, v131
	v_mfma_f32_16x16x32_bf16 v[56:59], v[218:221], v[52:55], v[56:59]
	s_waitcnt lgkmcnt(4)
	v_mfma_f32_16x16x32_bf16 v[100:103], v[222:225], v[68:71], v[64:67]
	v_mfma_f32_16x16x32_bf16 v[88:91], v[222:225], v[52:55], v[48:51]
	s_nop 1
	s_waitcnt lgkmcnt(2)
	v_mfma_f32_16x16x32_bf16 v[64:67], v[230:233], v[76:79], v[92:95]
	v_mfma_f32_16x16x32_bf16 v[48:51], v[230:233], v[60:63], v[80:83]
	s_nop 2
	s_waitcnt lgkmcnt(1)
	v_mfma_f32_16x16x32_bf16 v[72:75], v[234:237], v[76:79], v[72:75]
	v_mfma_f32_16x16x32_bf16 v[56:59], v[234:237], v[60:63], v[56:59]
	v_mfma_f32_16x16x32_bf16 v[68:71], v[226:229], v[76:79], v[96:99]
	v_mfma_f32_16x16x32_bf16 v[52:55], v[226:229], v[60:63], v[84:87]
	s_waitcnt lgkmcnt(0)
	v_mfma_f32_16x16x32_bf16 v[76:79], v[238:241], v[76:79], v[100:103]
	v_mfma_f32_16x16x32_bf16 v[60:63], v[238:241], v[60:63], v[88:91]

; DEVI unsigned pk_bf16(float lo, float hi) { unsigned r; asm("v_cvt_pk_bf16_f32 %0, %1, %2" : "=v"(r) : "v"(lo), "v"(hi)); return r; }
; DEVI bf16x8 mk8(uint2 a, uint2 b) { union { uint4 u; bf16x8 v; } c; c.u = make_uint4(a.x, a.y, b.x, b.y); return c.v; }
; template <int DK, bool BIAS> ...
;     ...
; #pragma unroll
;       for (int qi = 0; qi < 2; ++qi) {
;         float mx = -3e38f;
;         if (BIAS) {
; #pragma unroll
;           for (int kt = 0; kt < 4; ++kt) { const f32x4 nf = *(const f32x4*)(fkm + buf * 64 + 16 * kt + 4 * fq);
; #pragma unroll
;             for (int r = 0; r < 4; ++r) { const float t = fmaf(S[kt][qi][r], sc2, nf[r]); S[kt][qi][r] = t; mx = fmaxf(mx, t); } }
;         } else {
; #pragma unroll
;           for (int kt = 0; kt < 4; ++kt)
; #pragma unroll
;             for (int r = 0; r < 4; ++r) mx = fmaxf(mx, S[kt][qi][r]);
;           mx *= sc2;
;         }
;         mx = fmaxf(mx, __shfl_xor(mx, 16)); mx = fmaxf(mx, __shfl_xor(mx, 32));
;         const float mold = mrun[qi], mnew = fmaxf(mold, mx);
;         mrun[qi] = mnew;
;         float ps = 0.f;
; #pragma unroll
;         for (int kt = 0; kt < 4; ++kt)
; #pragma unroll
;           for (int r = 0; r < 4; ++r) { const float pv = BIAS ? __builtin_amdgcn_exp2f(S[kt][qi][r] - mnew) : __builtin_amdgcn_exp2f(fmaf(S[kt][qi][r], sc2, -mnew)); S[kt][qi][r] = pv; ps += pv; }
;         {
;           const float alpha = __builtin_amdgcn_exp2f(mold - mnew);
;           lrun[qi] *= alpha;
; #pragma unroll
;           for (int et = 0; et < 4; ++et) O[et][qi] *= alpha;
;         }
;         lrun[qi] += ps;
; #pragma unroll
;         for (int k2 = 0; k2 < 2; ++k2) { uint2 lo, hi; lo.x = pk_bf16(S[2 * k2][qi][0], S[2 * k2][qi][1]); lo.y = pk_bf16(S[2 * k2][qi][2], S[2 * k2][qi][3]);
;           hi.x = pk_bf16(S[2 * k2 + 1][qi][0], S[2 * k2 + 1][qi][1]); hi.y = pk_bf16(S[2 * k2 + 1][qi][2], S[2 * k2 + 1][qi][3]); pf[qi][k2] = mk8(lo, hi); }
;       }
; #pragma unroll
;       for (int k2 = 0; k2 < 2; ++k2)
; #pragma unroll
;         for (int et = 0; et < 4; ++et) {
;           const uint2 v0 = *(const uint2*)(Vtm + (buf * 64 + 16 * et + fr) * 72 + 32 * k2 + 4 * fq), v1 = *(const uint2*)(Vtm + (buf * 64 + 16 * et + fr) * 72 + 32 * k2 + 16 + 4 * fq);
;           const bf16x8 va = mk8(v0, v1);
.LBB0_1888:
	s_or_b64 exec, exec, s[18:19]
	s_mov_b32 s100, s34
	s_mov_b32 s101, s34
	v_lshlrev_b32_e32 v250, 2, v186
	v_max3_f32 v242, v96, s31, v97
	v_max3_f32 v243, v84, s31, v85
	v_max3_f32 v242, v242, v98, v99
	v_max3_f32 v243, v243, v86, v87
	v_max3_f32 v242, v242, v100, v101
	v_max3_f32 v243, v243, v88, v89
	v_max3_f32 v242, v242, v102, v103
	v_max3_f32 v243, v243, v90, v91
	v_max3_f32 v242, v242, v104, v105
	v_max3_f32 v243, v243, v80, v81
	v_max3_f32 v242, v242, v106, v107
	v_max3_f32 v243, v243, v82, v83
	v_max3_f32 v242, v242, v108, v109
	v_max3_f32 v243, v243, v92, v93
	v_max3_f32 v242, v242, v110, v111
	v_max3_f32 v243, v243, v94, v95
	v_mul_f32_e32 v242, 0x3e16c740, v242
	v_mul_f32_e32 v243, 0x3e16c740, v243
	ds_bpermute_b32 v244, v250, v242
	ds_bpermute_b32 v245, v250, v243
	s_waitcnt lgkmcnt(0)
	v_max_f32_e32 v242, v242, v244
	v_max_f32_e32 v243, v243, v245
	v_lshlrev_b32_e32 v250, 2, v185
	ds_bpermute_b32 v244, v250, v242
	ds_bpermute_b32 v245, v250, v243
	s_waitcnt lgkmcnt(0)
	v_max3_f32 v131, v154, v242, v244
	v_max3_f32 v209, v208, v243, v245
	v_sub_f32_e32 v242, v154, v131
	v_sub_f32_e32 v243, v208, v209
	v_sub_f32_e32 v246, 0, v131
	v_sub_f32_e32 v248, 0, v209
	v_pk_fma_f32 v[210:211], v[96:97], s[100:101], v[246:247] op_sel_hi:[1,1,0]
	v_pk_fma_f32 v[226:227], v[80:81], s[100:101], v[248:249] op_sel_hi:[1,1,0]
	v_pk_fma_f32 v[212:213], v[98:99], s[100:101], v[246:247] op_sel_hi:[1,1,0]
	v_pk_fma_f32 v[228:229], v[82:83], s[100:101], v[248:249] op_sel_hi:[1,1,0]
	v_pk_fma_f32 v[214:215], v[100:101], s[100:101], v[246:247] op_sel_hi:[1,1,0]
	v_pk_fma_f32 v[230:231], v[84:85], s[100:101], v[248:249] op_sel_hi:[1,1,0]
	v_pk_fma_f32 v[216:217], v[102:103], s[100:101], v[246:247] op_sel_hi:[1,1,0]
	v_pk_fma_f32 v[232:233], v[86:87], s[100:101], v[248:249] op_sel_hi:[1,1,0]
	v_pk_fma_f32 v[218:219], v[104:105], s[100:101], v[246:247] op_sel_hi:[1,1,0]
	v_pk_fma_f32 v[234:235], v[88:89], s[100:101], v[248:249] op_sel_hi:[1,1,0]
	v_pk_fma_f32 v[220:221], v[106:107], s[100:101], v[246:247] op_sel_hi:[1,1,0]
	v_pk_fma_f32 v[236:237], v[90:91], s[100:101], v[248:249] op_sel_hi:[1,1,0]
	v_pk_fma_f32 v[222:223], v[108:109], s[100:101], v[246:247] op_sel_hi:[1,1,0]
	v_pk_fma_f32 v[238:239], v[92:93], s[100:101], v[248:249] op_sel_hi:[1,1,0]
	v_pk_fma_f32 v[224:225], v[110:111], s[100:101], v[246:247] op_sel_hi:[1,1,0]
	v_pk_fma_f32 v[240:241], v[94:95], s[100:101], v[248:249] op_sel_hi:[1,1,0]
	v_exp_f32_e32 v178, v242
	v_exp_f32_e32 v90, v243
	v_exp_f32_e32 v163, v210
	v_exp_f32_e32 v162, v226
	v_exp_f32_e32 v165, v211
	v_exp_f32_e32 v164, v227
	v_exp_f32_e32 v167, v212
	v_exp_f32_e32 v166, v228
	v_exp_f32_e32 v169, v213
	v_exp_f32_e32 v168, v229
	v_exp_f32_e32 v155, v214
	v_exp_f32_e32 v170, v230
	v_exp_f32_e32 v157, v215
	v_exp_f32_e32 v104, v231
	v_exp_f32_e32 v159, v216
	v_exp_f32_e32 v172, v232
	v_exp_f32_e32 v161, v217
	v_exp_f32_e32 v106, v233
	v_exp_f32_e32 v171, v218
	v_exp_f32_e32 v154, v234
	v_exp_f32_e32 v105, v219
	v_exp_f32_e32 v156, v235
	v_exp_f32_e32 v173, v220
	v_exp_f32_e32 v158, v236
	v_exp_f32_e32 v107, v221
	v_exp_f32_e32 v160, v237
	v_exp_f32_e32 v175, v222
	v_exp_f32_e32 v174, v238
	v_exp_f32_e32 v109, v223
	v_exp_f32_e32 v108, v239
	v_exp_f32_e32 v177, v224
	v_exp_f32_e32 v176, v240
	v_exp_f32_e32 v111, v225
	v_exp_f32_e32 v110, v241
	v_add_u32_e32 v242, 0x6800, v206
	v_add_u32_e32 v243, 0x9000, v203
	v_add_u32_e32 v244, 0x9800, v203
	v_add_u32_e32 v245, 0xa000, v203
	ds_read2_b64 v[210:213], v242 offset1:4
	ds_read2_b64 v[214:217], v243 offset0:160 offset1:164
	ds_read2_b64 v[218:221], v244 offset0:192 offset1:196
	ds_read2_b64 v[222:225], v245 offset0:224 offset1:228
	ds_read2_b64 v[226:229], v243 offset0:168 offset1:172
	ds_read2_b64 v[230:233], v242 offset0:8 offset1:12
	ds_read2_b64 v[234:237], v244 offset0:200 offset1:204
	ds_read2_b64 v[238:241], v245 offset0:232 offset1:236
	v_pk_add_f32 v[80:81], v[154:155], 0 op_sel_hi:[1,0]
	v_pk_add_f32 v[80:81], v[156:157], v[80:81]
	v_pk_mul_f32 v[102:103], v[66:67], v[178:179] op_sel_hi:[1,0]
	v_pk_add_f32 v[80:81], v[158:159], v[80:81]
	v_pk_mul_f32 v[100:101], v[64:65], v[178:179] op_sel_hi:[1,0]
	v_pk_add_f32 v[80:81], v[160:161], v[80:81]
	v_pk_mul_f32 v[64:65], v[76:77], v[178:179] op_sel_hi:[1,0]
	v_pk_add_f32 v[80:81], v[162:163], v[80:81]
	v_cvt_pk_bf16_f32 v76, v171, v105
	v_pk_mul_f32 v[98:99], v[70:71], v[178:179] op_sel_hi:[1,0]
	v_pk_add_f32 v[80:81], v[164:165], v[80:81]
	v_pk_mul_f32 v[96:97], v[68:69], v[178:179] op_sel_hi:[1,0]
	v_pk_add_f32 v[88:89], v[166:167], v[80:81]
	v_cvt_pk_bf16_f32 v68, v155, v157
	v_cvt_pk_bf16_f32 v69, v159, v161
	v_cvt_pk_bf16_f32 v70, v163, v165
	v_cvt_pk_bf16_f32 v71, v167, v169
	v_pk_mul_f32 v[74:75], v[74:75], v[178:179] op_sel_hi:[1,0]
	v_pk_mul_f32 v[84:85], v[52:53], v[90:91] op_sel_hi:[1,0]
	v_pk_add_f32 v[52:53], v[168:169], v[88:89]
	v_pk_mul_f32 v[82:83], v[50:51], v[90:91] op_sel_hi:[1,0]
	v_pk_add_f32 v[52:53], v[170:171], v[52:53]
	v_pk_mul_f32 v[80:81], v[48:49], v[90:91] op_sel_hi:[1,0]
	v_pk_add_f32 v[52:53], v[104:105], v[52:53]
	v_pk_mul_f32 v[86:87], v[54:55], v[90:91] op_sel_hi:[1,0]
	v_pk_add_f32 v[52:53], v[172:173], v[52:53]
	v_pk_mul_f32 v[58:59], v[58:59], v[90:91] op_sel_hi:[1,0]
	v_pk_add_f32 v[52:53], v[106:107], v[52:53]
	v_pk_mul_f32 v[56:57], v[56:57], v[90:91] op_sel_hi:[1,0]
	v_pk_add_f32 v[52:53], v[174:175], v[52:53]
	v_pk_mul_f32 v[50:51], v[62:63], v[90:91] op_sel_hi:[1,0]
	v_pk_add_f32 v[52:53], v[108:109], v[52:53]
	v_pk_mul_f32 v[48:49], v[60:61], v[90:91] op_sel_hi:[1,0]
	v_pk_add_f32 v[52:53], v[176:177], v[52:53]
	v_mov_b32_e32 v91, v178
	v_pk_add_f32 v[52:53], v[110:111], v[52:53]
	v_cvt_pk_bf16_f32 v60, v170, v104
	v_pk_fma_f32 v[120:121], v[120:121], v[90:91], v[52:53]
	v_cvt_pk_bf16_f32 v52, v154, v156
	v_cvt_pk_bf16_f32 v53, v158, v160
	v_cvt_pk_bf16_f32 v54, v162, v164
	v_cvt_pk_bf16_f32 v55, v166, v168
	s_waitcnt lgkmcnt(7)
; DEVI unsigned pk_bf16(float lo, float hi) { unsigned r; asm("v_cvt_pk_bf16_f32 %0, %1, %2" : "=v"(r) : "v"(lo), "v"(hi)); return r; }
; DEVI bf16x8 mk8(uint2 a, uint2 b) { union { uint4 u; bf16x8 v; } c; c.u = make_uint4(a.x, a.y, b.x, b.y); return c.v; }
; #define MFMA(a, b, c) __builtin_amdgcn_mfma_f32_16x16x32_bf16((a), (b), (c), 0, 0, 0)
; template <int DK, bool BIAS> ...
;     ...
;         for (int k2 = 0; k2 < 2; ++k2) { uint2 lo, hi; lo.x = pk_bf16(S[2 * k2][qi][0], S[2 * k2][qi][1]); lo.y = pk_bf16(S[2 * k2][qi][2], S[2 * k2][qi][3]);
;           hi.x = pk_bf16(S[2 * k2 + 1][qi][0], S[2 * k2 + 1][qi][1]); hi.y = pk_bf16(S[2 * k2 + 1][qi][2], S[2 * k2 + 1][qi][3]); pf[qi][k2] = mk8(lo, hi); }
;       }
; #pragma unroll
;       for (int k2 = 0; k2 < 2; ++k2)
; #pragma unroll
;         for (int et = 0; et < 4; ++et) {
;           const uint2 v0 = *(const uint2*)(Vtm + (buf * 64 + 16 * et + fr) * 72 + 32 * k2 + 4 * fq), v1 = *(const uint2*)(Vtm + (buf * 64 + 16 * et + fr) * 72 + 32 * k2 + 16 + 4 * fq);
;           const bf16x8 va = mk8(v0, v1);
; #pragma unroll
;           for (int qi = 0; qi < 2; ++qi) O[et][qi] = MFMA(va, pf[qi][k2], O[et][qi]);
;         }
	v_mfma_f32_16x16x32_bf16 v[92:95], v[210:213], v[68:71], v[100:103]
	v_cvt_pk_bf16_f32 v61, v172, v106
	v_pk_mul_f32 v[72:73], v[72:73], v[178:179] op_sel_hi:[1,0]
	v_mfma_f32_16x16x32_bf16 v[80:83], v[210:213], v[52:55], v[80:83]
	v_cvt_pk_bf16_f32 v77, v173, v107
	s_waitcnt lgkmcnt(6)
	v_mfma_f32_16x16x32_bf16 v[96:99], v[214:217], v[68:71], v[96:99]
	v_pk_mul_f32 v[66:67], v[78:79], v[178:179] op_sel_hi:[1,0]
	v_cvt_pk_bf16_f32 v78, v175, v109
	v_cvt_pk_bf16_f32 v79, v177, v111
	v_mfma_f32_16x16x32_bf16 v[84:87], v[214:217], v[52:55], v[84:87]
	v_cvt_pk_bf16_f32 v62, v174, v108
	v_cvt_pk_bf16_f32 v63, v176, v110
	s_waitcnt lgkmcnt(5)
	v_mfma_f32_16x16x32_bf16 v[72:75], v[218:221], v[68:71], v[72:75]
	v_mov_b32_e32 v208, v209
	v_mov_b32_e32 v154, v131
	v_mfma_f32_16x16x32_bf16 v[56:59], v[218:221], v[52:55], v[56:59]
	s_waitcnt lgkmcnt(4)
	v_mfma_f32_16x16x32_bf16 v[100:103], v[222:225], v[68:71], v[64:67]
	v_mfma_f32_16x16x32_bf16 v[88:91], v[222:225], v[52:55], v[48:51]
	s_nop 1
	s_waitcnt lgkmcnt(2)
	v_mfma_f32_16x16x32_bf16 v[64:67], v[230:233], v[76:79], v[92:95]
	v_mfma_f32_16x16x32_bf16 v[48:51], v[230:233], v[60:63], v[80:83]
	s_nop 2
	s_waitcnt lgkmcnt(1)
	v_mfma_f32_16x16x32_bf16 v[72:75], v[234:237], v[76:79], v[72:75]
	v_mfma_f32_16x16x32_bf16 v[56:59], v[234:237], v[60:63], v[56:59]
	v_mfma_f32_16x16x32_bf16 v[68:71], v[226:229], v[76:79], v[96:99]
	v_mfma_f32_16x16x32_bf16 v[52:55], v[226:229], v[60:63], v[84:87]
	s_waitcnt lgkmcnt(0)
	v_mfma_f32_16x16x32_bf16 v[76:79], v[238:241], v[76:79], v[100:103]
	v_mfma_f32_16x16x32_bf16 v[60:63], v[238:241], v[60:63], v[88:91]
